# unit descriptor: tile-order division by the 8-row group done as a shift; PH2 loop SGPR-base DMA addressing; LDS read addresses folded into offsets
# baseline (speedup 1.0000x reference)
;     __device__ __forceinline__ bool next(int i, Unit& u) const {
;     ...
;             if (L >= 768) return false; pg8::tile_order(L, 32, 24, u.pm, u.pn);
;             u.A = (const char*)P.xb_() + (size_t)u.pm * 256 * 4096; u.B = (const char*)P.win_() + (size_t)u.pn * 256 * 4096; u.lda = 4096; u.ldb = 4096; u.nt = 32;
;             u.kind = u.pn < 2 ? K_QLAT : u.pn < 4 ? K_KVLAT : u.pn < 8 ? K_U : K_GATES; return true;
.LBB0_243:
	s_add_i32 s79, s79, 1
	s_mul_i32 s12, s79, s92
	s_add_i32 s12, s12, s2
	s_cmpk_lt_i32 s12, 0x300
	s_cselect_b64 s[30:31], -1, 0
	s_cmpk_gt_i32 s12, 0x2ff
	s_cbranch_scc1 .LBB0_245
	s_ashr_i32 s22, s12, 31
	s_lshr_b32 s22, s22, 29
	s_add_i32 s22, s12, s22
	s_ashr_i32 s23, s22, 3
	s_and_b32 s22, s22, -8
	s_sub_i32 s12, s12, s22
	s_lshr_b32 s22, s12, 31
	s_or_b32 s22, s22, 0x60
	s_mul_i32 s12, s22, s12
	s_add_i32 s12, s12, s23
	s_mul_hi_i32 s22, s12, 0x2aaaaaab
	s_lshr_b32 s23, s22, 31
	s_ashr_i32 s22, s22, 5
	s_add_i32 s22, s22, s23
	s_lshl_b32 s28, s22, 3
	s_sub_i32 s23, 32, s28
	s_min_u32 s29, s23, 8
	s_mulk_i32 s22, 0xc0
	s_sub_i32 s33, s12, s22
	s_waitcnt lgkmcnt(0)
	s_ashr_i32 s12, s33, 3
	s_mul_i32 s22, s12, s29
	s_sub_i32 s22, s33, s22
	s_sext_i32_i16 s22, s22
	s_add_i32 s22, s28, s22
	s_ashr_i32 s23, s22, 31
	s_lshl_b64 s[28:29], s[22:23], 20
	s_add_u32 s28, s66, s28
	s_addc_u32 s29, s67, s29
	s_bfe_i64 s[36:37], s[12:13], 0x100000
	s_lshl_b64 s[36:37], s[36:37], 20
	s_add_u32 s36, s68, s36
	s_sext_i32_i16 s80, s12
	s_addc_u32 s37, s69, s37
	s_and_b32 s12, s12, 0xffff
	s_cmp_lt_u32 s12, 8
	s_cselect_b32 s23, 2, 3
	s_cmp_gt_u32 s12, 3
	s_cselect_b32 s12, s23, 1
	s_cmp_gt_i32 s80, 1
	s_cselect_b32 s23, s12, 0

;     __device__ __forceinline__ bool next(int i, Unit& u) const {
;     ...
;             const int T = c + G * (i / 3), sub = i % 3; if (T >= 32 * 8) return false; int tm, tn; pg8::tile_order(T, 32, 8, tm, tn); u.pm = tm;
;             if (sub < 2) { u.pn = 2 * tn + sub; u.kind = K_GLU; u.A = (const char*)P.y_() + (size_t)u.pm * 256 * 2048; u.B = (const char*)P.wglu_() + (size_t)u.pn * 256 * 2048; u.lda = 2048; u.ldb = 2048; u.nt = 16; return true; }
;             u.pn = tn; u.kind = K_AP; u.A = (const char*)P.o_() + (size_t)u.pm * 256 * 4096; u.B = (const char*)P.wap_() + (size_t)u.pn * 256 * 4096; u.lda = 4096; u.ldb = 4096; u.nt = 32; return true;
.LBB0_798:
	s_add_i32 s79, s79, 1
	s_mul_hi_u32 s6, s79, 0xaaaaaaab
	s_lshr_b32 s44, s6, 1
	s_mul_i32 s6, s44, s92
	s_add_i32 s6, s6, s2
	s_cmpk_lt_i32 s6, 0x100
	s_cselect_b64 s[36:37], -1, 0
	s_cmpk_gt_i32 s6, 0xff
	s_mov_b32 s80, s56
	s_cbranch_scc1 .LBB0_805
	s_ashr_i32 s22, s6, 31
	s_lshr_b32 s22, s22, 29
	s_add_i32 s22, s6, s22
	s_ashr_i32 s28, s22, 3
	s_and_b32 s22, s22, -8
	s_sub_i32 s6, s6, s22
	s_lshr_b32 s22, s6, 31
	s_or_b32 s22, s22, 32
	s_mul_i32 s6, s22, s6
	s_add_i32 s6, s6, s28
	s_ashr_i32 s22, s6, 31
	s_lshr_b32 s22, s22, 26
	s_add_i32 s22, s6, s22
	s_ashr_i32 s28, s22, 6
	s_lshl_b32 s30, s28, 3
	s_sub_i32 s28, 32, s30
	s_min_u32 s31, s28, 8
	s_andn2_b32 s22, s22, 63
	s_sub_i32 s22, s6, s22
	s_mul_i32 s44, s44, 3
	s_sub_i32 s6, s79, s44
	s_ashr_i32 s44, s22, 3
	s_mul_i32 s28, s44, s31
	s_sub_i32 s22, s22, s28
	s_sext_i32_i8 s22, s22
	s_add_i32 s28, s30, s22
	s_cmp_gt_u32 s6, 1
	s_mov_b64 s[38:39], -1
	s_cbranch_scc0 .LBB0_801
	s_ashr_i32 s29, s28, 31
	s_lshl_b64 s[30:31], s[28:29], 20
	v_mov_b32_e32 v2, s44
	s_add_u32 s30, s70, s30
	v_readfirstlane_b32 s22, v2
	s_addc_u32 s31, s71, s31
	s_bfe_i64 s[38:39], s[22:23], 0x80000
	s_lshl_b64 s[38:39], s[38:39], 20
	s_add_u32 s40, s72, s38
	s_addc_u32 s41, s73, s39
	s_mov_b64 s[38:39], 0

;     __device__ __forceinline__ bool next(int i, Unit& u) const {
;     ...
;             if (L >= 32 * 8) return false; pg8::tile_order(L, 32, 8, u.pm, u.pn); u.kind = PH == 6 ? K_AP : K_OUT;
;             u.A = (const char*)(PH == 6 ? P.o_() : P.mixed_()) + (size_t)u.pm * 256 * 4096; u.B = (const char*)(PH == 6 ? P.wap_() : P.wout_()) + (size_t)u.pn * 256 * 4096; u.lda = 4096; u.ldb = 4096; u.nt = 32; return true;
.LBB0_891:
	s_add_i32 s54, s54, 1
	s_mul_i32 s19, s54, s92
	s_add_i32 s19, s19, s2
	s_cmpk_lt_i32 s19, 0x100
	s_cselect_b64 s[22:23], -1, 0
	s_cmpk_gt_i32 s19, 0xff
	s_cbranch_scc1 .LBB0_893
	s_ashr_i32 s18, s19, 31
	s_lshr_b32 s18, s18, 29
	s_add_i32 s18, s19, s18
	s_ashr_i32 s20, s18, 3
	s_and_b32 s18, s18, -8
	s_sub_i32 s18, s19, s18
	s_lshr_b32 s19, s18, 31
	s_or_b32 s19, s19, 32
	s_mul_i32 s18, s19, s18
	s_add_i32 s18, s18, s20
	s_ashr_i32 s19, s18, 31
	s_lshr_b32 s19, s19, 26
	s_add_i32 s19, s18, s19
	s_ashr_i32 s20, s19, 6
	s_lshl_b32 s20, s20, 3
	s_sub_i32 s21, 32, s20
	s_min_u32 s21, s21, 8
	s_andn2_b32 s19, s19, 63
	s_sub_i32 s29, s18, s19
	s_waitcnt lgkmcnt(0)
	s_ashr_i32 s28, s29, 3
	s_mul_i32 s18, s28, s21
	s_sub_i32 s18, s29, s18
	s_sext_i32_i8 s18, s18
	s_add_i32 s18, s20, s18
	s_ashr_i32 s19, s18, 31
	s_lshl_b64 s[20:21], s[18:19], 20
	s_add_u32 s20, s57, s20
	s_sext_i32_i8 s63, s28
	s_addc_u32 s21, s58, s21
	s_bfe_i64 s[28:29], s[28:29], 0x80000
	s_lshl_b64 s[28:29], s[28:29], 20
	s_add_u32 s28, s59, s28
	s_addc_u32 s29, s60, s29

;     __device__ __forceinline__ bool next(int i, Unit& u) const {
;     ...
;         } else if constexpr (PH == 8) {
;             if (L >= 32 * 44) return false; pg8::tile_order(L, 32, 44, u.pm, u.pn); u.kind = K_FFN;
;             u.A = (const char*)P.h1b_() + (size_t)u.pm * 256 * 4096; u.B = (const char*)P.wffn_() + (size_t)u.pn * 256 * 4096; u.lda = 4096; u.ldb = 4096; u.nt = 32; return true;
.LBB0_996:
	s_add_i32 s46, s46, 1
	s_mul_i32 s15, s46, s92
	s_add_i32 s15, s15, s2
	s_cmpk_lt_i32 s15, 0x580
	s_cselect_b64 s[18:19], -1, 0
	s_cmpk_gt_i32 s15, 0x57f
	s_cbranch_scc1 .LBB0_998
	s_ashr_i32 s14, s15, 31
	s_lshr_b32 s14, s14, 29
	s_add_i32 s14, s15, s14
	s_ashr_i32 s16, s14, 3
	s_and_b32 s14, s14, -8
	s_sub_i32 s14, s15, s14
	s_lshr_b32 s15, s14, 31
	s_or_b32 s15, s15, 0xb0
	s_mul_i32 s14, s15, s14
	s_add_i32 s14, s14, s16
	s_mul_hi_i32 s15, s14, 0x2e8ba2e9
	s_lshr_b32 s16, s15, 31
	s_ashr_i32 s15, s15, 6
	s_add_i32 s15, s15, s16
	s_lshl_b32 s16, s15, 3
	s_sub_i32 s17, 32, s16
	s_min_u32 s17, s17, 8
	s_mulk_i32 s15, 0x160
	s_sub_i32 s21, s14, s15
	s_ashr_i32 s20, s21, 3
	s_mul_i32 s14, s20, s17
	s_sub_i32 s14, s21, s14
	s_sext_i32_i16 s14, s14
	s_add_i32 s14, s16, s14
	s_ashr_i32 s15, s14, 31
	s_lshl_b64 s[16:17], s[14:15], 20
	s_add_u32 s16, s33, s16
	s_sext_i32_i16 s53, s20
	s_addc_u32 s17, s35, s17
	s_bfe_i64 s[20:21], s[20:21], 0x100000
	s_lshl_b64 s[20:21], s[20:21], 20
	s_add_u32 s20, s40, s20
	s_addc_u32 s21, s41, s21

;     __device__ __forceinline__ bool next(int i, Unit& u) const {
;     ...
;             if (L >= 32 * 8) return false; pg8::tile_order(L, 32, 8, u.pm, u.pn); u.kind = K_DOWN;
;             u.A = (const char*)P.f_() + (size_t)u.pm * 256 * (DFF * 2); u.B = (const char*)P.wdown_() + (size_t)u.pn * 256 * (DFF * 2); u.lda = DFF * 2; u.ldb = DFF * 2; u.nt = DFF / 64; return true;
.LBB0_1121:
	s_add_i32 s42, s42, 1
	s_mul_i32 s36, s42, s92
	s_add_i32 s36, s36, s2
	s_cmpk_lt_i32 s36, 0x100
	s_cselect_b64 s[20:21], -1, 0
	s_cmpk_gt_i32 s36, 0xff
	s_cbranch_scc1 .LBB0_1123
	s_ashr_i32 s18, s36, 31
	s_lshr_b32 s18, s18, 29
	s_add_i32 s18, s36, s18
	s_ashr_i32 s19, s18, 3
	s_and_b32 s18, s18, -8
	s_sub_i32 s18, s36, s18
	s_lshr_b32 s22, s18, 31
	s_or_b32 s22, s22, 32
	s_mul_i32 s18, s22, s18
	s_add_i32 s18, s18, s19
	s_ashr_i32 s19, s18, 31
	s_lshr_b32 s19, s19, 26
	s_add_i32 s19, s18, s19
	s_ashr_i32 s22, s19, 6
	s_lshl_b32 s23, s22, 3
	s_sub_i32 s22, 32, s23
	s_min_u32 s36, s22, 8
	s_andn2_b32 s19, s19, 63
	s_sub_i32 s37, s18, s19
	s_waitcnt lgkmcnt(0)
	s_ashr_i32 s22, s37, 3
	s_mul_i32 s18, s22, s36
	s_sub_i32 s18, s37, s18
	s_sext_i32_i8 s18, s18
	s_add_i32 s52, s23, s18
	s_mul_i32 s18, s52, 0x2c0000
	s_mul_hi_i32 s19, s52, 0x2c0000
	s_add_u32 s18, s45, s18
	s_sext_i32_i8 s51, s22
	s_addc_u32 s19, s46, s19
	s_bfe_i64 s[22:23], s[22:23], 0x80000
	s_mul_hi_i32 s23, s22, 0x2c0000
	s_mul_i32 s22, s22, 0x2c0000
	s_add_u32 s22, s47, s22
	s_addc_u32 s23, s48, s23
